# grid barrier: the first block of each XCD to arrive starts an L2 write-back early
# baseline (speedup 1.0000x reference)
.LBB0_63:
	s_or_b64 exec, exec, s[4:5]
	v_cvt_f32_u32_e32 v4, v2
	s_waitcnt vmcnt(0)
	v_readfirstlane_b32 s0, v3
	v_sub_u32_e32 v3, 0, v2
	v_rcp_iflag_f32_e32 v4, v4
	v_add_u32_e32 v5, s0, v1
	v_mul_f32_e32 v4, 0x4f7ffffe, v4
	v_cvt_u32_f32_e32 v4, v4
	v_mul_lo_u32 v1, v3, v4
	v_mul_hi_u32 v1, v4, v1
	v_add_u32_e32 v1, v4, v1
	v_mul_hi_u32 v1, v5, v1
	v_mul_lo_u32 v3, v1, v2
	v_sub_u32_e32 v3, v5, v3
	v_add_u32_e32 v4, 1, v1
	v_cmp_ge_u32_e32 vcc, v3, v2
	s_nop 1
	v_cndmask_b32_e32 v1, v1, v4, vcc
	v_sub_u32_e32 v4, v3, v2
	v_cndmask_b32_e32 v3, v3, v4, vcc
	v_add_u32_e32 v4, 1, v1
	v_cmp_ge_u32_e32 vcc, v3, v2
	v_add_u32_e32 v3, 1, v5
	s_nop 0
	v_cndmask_b32_e32 v1, v1, v4, vcc
	v_mul_lo_u32 v4, v2, v1
	v_add_u32_e32 v2, v4, v2
	v_cmp_eq_u32_e32 vcc, v5, v4
	s_and_saveexec_b64 s[0:1], vcc
	s_cbranch_execz .Lxb_first0
	buffer_wbl2 sc1
.Lxb_first0:
	s_or_b64 exec, exec, s[0:1]
	v_cmp_ne_u32_e32 vcc, v3, v2
	s_and_saveexec_b64 s[0:1], vcc
	s_xor_b64 s[4:5], exec, s[0:1]
	s_cbranch_execz .LBB0_77
	s_waitcnt lgkmcnt(0)
	v_mov_b32_e32 v0, 0x2000
	global_load_dword v0, v0, s[8:9] offset:1024 sc1
	s_add_u32 s12, s8, 0x2400
	s_addc_u32 s13, s9, 0
	s_waitcnt vmcnt(0)
	v_cmp_eq_u32_e32 vcc, v0, v1
	s_and_saveexec_b64 s[0:1], vcc
	s_cbranch_execz .LBB0_76
	s_add_u32 s10, s26, 0xc0200
	s_addc_u32 s11, s27, 0
	s_mov_b32 s23, 1
	s_mov_b64 s[14:15], 0
	v_mov_b32_e32 v0, 0
	s_branch .LBB0_67

.Lxb_first2:
	s_or_b64 exec, exec, s[0:1]
	v_cmp_ne_u32_e32 vcc, v3, v2
	s_and_saveexec_b64 s[0:1], vcc
	s_xor_b64 s[4:5], exec, s[0:1]
	s_cbranch_execz .LBB0_506
	s_waitcnt lgkmcnt(0)
	v_mov_b32_e32 v0, 0x2000
	global_load_dword v0, v0, s[8:9] offset:1024 sc1
	s_add_u32 s12, s8, 0x2400
	s_addc_u32 s13, s9, 0
	s_waitcnt vmcnt(0)
	v_cmp_eq_u32_e32 vcc, v0, v1
	s_and_saveexec_b64 s[0:1], vcc
	s_cbranch_execz .LBB0_505
	s_add_u32 s10, s26, 0xc0200
	s_addc_u32 s11, s27, 0
	s_mov_b32 s20, 1
	s_mov_b64 s[14:15], 0
	v_mov_b32_e32 v0, 0
	s_branch .LBB0_496

.Lxb_first5:
	s_or_b64 exec, exec, s[0:1]
	v_cmp_ne_u32_e32 vcc, v3, v2
	s_and_saveexec_b64 s[0:1], vcc
	s_xor_b64 s[4:5], exec, s[0:1]
	s_cbranch_execz .LBB0_819
	s_waitcnt lgkmcnt(0)
	v_mov_b32_e32 v0, 0x2000
	global_load_dword v0, v0, s[10:11] offset:1024 sc1
	s_add_u32 s14, s10, 0x2400
	s_addc_u32 s15, s11, 0
	s_waitcnt vmcnt(0)
	v_cmp_eq_u32_e32 vcc, v0, v1
	s_and_saveexec_b64 s[0:1], vcc
	s_cbranch_execz .LBB0_818
	s_add_u32 s12, s26, 0xc0200
	s_addc_u32 s13, s27, 0
	s_mov_b32 s20, 1
	s_mov_b64 s[16:17], 0
	v_mov_b32_e32 v0, 0
	s_branch .LBB0_809

.LBB0_1772:
	s_or_b64 exec, exec, s[6:7]
	v_cvt_f32_u32_e32 v4, v2
	s_waitcnt vmcnt(0)
	v_readfirstlane_b32 s0, v3
	v_sub_u32_e32 v3, 0, v2
	v_rcp_iflag_f32_e32 v4, v4
	v_add_u32_e32 v5, s0, v1
	v_mul_f32_e32 v4, 0x4f7ffffe, v4
	v_cvt_u32_f32_e32 v4, v4
	v_mul_lo_u32 v1, v3, v4
	v_mul_hi_u32 v1, v4, v1
	v_add_u32_e32 v1, v4, v1
	v_mul_hi_u32 v1, v5, v1
	v_mul_lo_u32 v3, v1, v2
	v_sub_u32_e32 v3, v5, v3
	v_add_u32_e32 v4, 1, v1
	v_cmp_ge_u32_e32 vcc, v3, v2
	s_nop 1
	v_cndmask_b32_e32 v1, v1, v4, vcc
	v_sub_u32_e32 v4, v3, v2
	v_cndmask_b32_e32 v3, v3, v4, vcc
	v_add_u32_e32 v4, 1, v1
	v_cmp_ge_u32_e32 vcc, v3, v2
	v_add_u32_e32 v3, 1, v5
	s_nop 0
	v_cndmask_b32_e32 v1, v1, v4, vcc
	v_mul_lo_u32 v4, v2, v1
	v_add_u32_e32 v2, v4, v2
	v_cmp_eq_u32_e32 vcc, v5, v4
	s_and_saveexec_b64 s[0:1], vcc
	s_cbranch_execz .Lxb_first18
	buffer_wbl2 sc1
.Lxb_first18:
	s_or_b64 exec, exec, s[0:1]
	v_cmp_ne_u32_e32 vcc, v3, v2
	s_and_saveexec_b64 s[0:1], vcc
	s_xor_b64 s[0:1], exec, s[0:1]
	s_cbranch_execz .LBB0_1786
	s_waitcnt lgkmcnt(0)
	v_mov_b32_e32 v0, 0x2000
	global_load_dword v0, v0, s[4:5] offset:1024 sc1
	s_add_u32 s10, s4, 0x2400
	s_addc_u32 s11, s5, 0
	s_waitcnt vmcnt(0)
	v_cmp_eq_u32_e32 vcc, v0, v1
	s_and_saveexec_b64 s[6:7], vcc
	s_cbranch_execz .LBB0_1785
	s_add_u32 s8, s26, 0xc0200
	s_addc_u32 s9, s27, 0
	s_mov_b32 s23, 1
	s_mov_b64 s[12:13], 0
	v_mov_b32_e32 v0, 0
	s_branch .LBB0_1776
